# v35 + row sums of squares in the fused norm epilogues exchanged with permlane16/32 swaps instead of ds_bpermute round trips
# baseline (speedup 1.0000x reference)
.LBB0_51:
	s_lshl_b32 s68, s8, 7
	s_lshl_b32 s70, s66, 8
	v_add_u32_e32 v156, s68, v165
	s_ashr_i32 s71, s70, 31
	v_ashrrev_i32_e32 v157, 31, v156
	v_lshl_add_u64 v[68:69], s[70:71], 1, v[140:141]
	v_lshlrev_b64 v[146:147], 11, v[156:157]
	v_lshl_add_u64 v[70:71], v[68:69], 0, v[146:147]
	global_load_dwordx4 v[80:83], v[70:71], off offset:16
	global_load_dwordx4 v[112:115], v[70:71], off
	v_or_b32_e32 v70, 16, v156
	s_add_i32 s4, s68, 0xfffff000
	v_ashrrev_i32_e32 v71, 31, v70
	s_ashr_i32 s4, s4, 10
	v_lshlrev_b64 v[70:71], 11, v[70:71]
	s_add_i32 s4, s4, 1
	v_lshl_add_u64 v[70:71], v[68:69], 0, v[70:71]
	global_load_dwordx4 v[76:79], v[70:71], off offset:16
	global_load_dwordx4 v[108:111], v[70:71], off
	v_or_b32_e32 v70, 32, v156
	s_cmp_gt_i32 s8, 31
	v_readlane_b32 s2, v254, 57
	v_ashrrev_i32_e32 v71, 31, v70
	s_cselect_b32 s9, s4, 0
	s_mul_i32 s4, s2, 5
	v_lshlrev_b64 v[70:71], 11, v[70:71]
	s_add_i32 s9, s9, s4
	v_lshl_add_u64 v[70:71], v[68:69], 0, v[70:71]
	s_mul_i32 s5, s9, 0x6000
	global_load_dwordx4 v[72:75], v[70:71], off offset:16
	global_load_dwordx4 v[104:107], v[70:71], off
	v_or_b32_e32 v70, 48, v156
	s_mul_hi_i32 s4, s9, 0x6000
	s_add_u32 s5, s83, s5
	v_or_b32_e32 v158, s70, v164
	v_ashrrev_i32_e32 v71, 31, v70
	s_addc_u32 s20, s84, s4
	v_ashrrev_i32_e32 v159, 31, v158
	v_lshlrev_b64 v[70:71], 11, v[70:71]
	s_add_u32 s4, s5, 0x5000
	v_or_b32_e32 v150, 16, v158
	v_or_b32_e32 v152, 0x80, v158
	v_or_b32_e32 v154, 0x90, v158
	v_lshl_add_u64 v[84:85], v[68:69], 0, v[70:71]
	s_addc_u32 s5, s20, 0
	v_lshlrev_b64 v[148:149], 2, v[158:159]
	v_ashrrev_i32_e32 v151, 31, v150
	v_ashrrev_i32_e32 v153, 31, v152
	v_ashrrev_i32_e32 v155, 31, v154
	global_load_dwordx4 v[68:71], v[84:85], off offset:16
	global_load_dwordx4 v[100:103], v[84:85], off
	v_lshl_add_u64 v[84:85], s[6:7], 0, v[148:149]
	v_lshl_add_u64 v[86:87], s[4:5], 0, v[148:149]
	v_lshl_add_u64 v[88:89], v[150:151], 2, s[4:5]
	v_lshl_add_u64 v[92:93], v[152:153], 2, s[4:5]
	v_lshl_add_u64 v[94:95], v[154:155], 2, s[4:5]
	global_load_dwordx4 v[116:119], v[84:85], off
	global_load_dwordx4 v[120:123], v[84:85], off offset:64
	global_load_dwordx4 v[128:131], v[86:87], off
	global_load_dwordx4 v[124:127], v[88:89], off
	s_nop 0
	global_load_dwordx4 v[88:91], v[84:85], off offset:512
	s_nop 0
	global_load_dwordx4 v[84:87], v[84:85], off offset:576
	s_nop 0
	global_load_dwordx4 v[96:99], v[92:93], off
	s_nop 0
	global_load_dwordx4 v[92:95], v[94:95], off
	v_mul_f32_e32 v0, v61, v61
	v_mul_f32_e32 v1, v63, v63
	v_fmac_f32_e32 v0, v60, v60
	v_fmac_f32_e32 v1, v62, v62
	v_add_f32_e32 v0, v0, v1
	v_mul_f32_e32 v1, v65, v65
	v_mul_f32_e32 v2, v67, v67
	v_fmac_f32_e32 v1, v64, v64
	v_fmac_f32_e32 v2, v66, v66
	v_add_f32_e32 v1, v1, v2
	v_add_f32_e32 v0, v0, v1
	v_mul_f32_e32 v1, v33, v33
	v_mul_f32_e32 v2, v35, v35
	v_fmac_f32_e32 v1, v32, v32
	v_fmac_f32_e32 v2, v34, v34
	v_add_f32_e32 v1, v1, v2
	v_add_f32_e32 v0, v0, v1
	v_mul_f32_e32 v1, v29, v29
	v_mul_f32_e32 v2, v31, v31
	v_fmac_f32_e32 v1, v28, v28
	v_fmac_f32_e32 v2, v30, v30
	v_add_f32_e32 v1, v1, v2
	v_add_f32_e32 v0, v0, v1
	v_mov_b32_e32 v1, v0
	s_nop 1
	v_permlane16_swap_b32_e32 v0, v1
	v_add_f32_e32 v2, v0, v1
	v_mov_b32_e32 v178, v2
	s_nop 1
	v_permlane32_swap_b32_e32 v2, v178
	s_and_saveexec_b64 s[4:5], s[38:39]
	s_cbranch_execz .LBB0_53
	v_add_f32_e32 v0, v2, v178
	ds_write_b32 v172, v0
.LBB0_53:
	s_or_b64 exec, exec, s[4:5]
	v_mul_f32_e32 v0, v57, v57
	v_mul_f32_e32 v1, v59, v59
	v_fmac_f32_e32 v0, v56, v56
	v_fmac_f32_e32 v1, v58, v58
	v_add_f32_e32 v0, v0, v1
	v_mul_f32_e32 v1, v53, v53
	v_mul_f32_e32 v2, v55, v55
	v_fmac_f32_e32 v1, v52, v52
	v_fmac_f32_e32 v2, v54, v54
	v_add_f32_e32 v1, v1, v2
	v_add_f32_e32 v0, v0, v1
	v_mul_f32_e32 v1, v25, v25
	v_mul_f32_e32 v2, v27, v27
	v_fmac_f32_e32 v1, v24, v24
	v_fmac_f32_e32 v2, v26, v26
	v_add_f32_e32 v1, v1, v2
	v_add_f32_e32 v0, v0, v1
	v_mul_f32_e32 v1, v21, v21
	v_mul_f32_e32 v2, v23, v23
	v_fmac_f32_e32 v1, v20, v20
	v_fmac_f32_e32 v2, v22, v22
	v_add_f32_e32 v1, v1, v2
	v_add_f32_e32 v0, v0, v1
	v_mov_b32_e32 v1, v0
	s_nop 1
	v_permlane16_swap_b32_e32 v0, v1
	v_add_f32_e32 v2, v0, v1
	v_mov_b32_e32 v178, v2
	s_nop 1
	v_permlane32_swap_b32_e32 v2, v178
	s_and_saveexec_b64 s[4:5], s[38:39]
	s_cbranch_execz .LBB0_55
	v_add_f32_e32 v0, v2, v178
	ds_write_b32 v172, v0 offset:256
.LBB0_55:
	s_or_b64 exec, exec, s[4:5]
	v_mul_f32_e32 v0, v49, v49
	v_mul_f32_e32 v1, v51, v51
	v_fmac_f32_e32 v0, v48, v48
	v_fmac_f32_e32 v1, v50, v50
	v_add_f32_e32 v0, v0, v1
	v_mul_f32_e32 v1, v45, v45
	v_mul_f32_e32 v2, v47, v47
	v_fmac_f32_e32 v1, v44, v44
	v_fmac_f32_e32 v2, v46, v46
	v_add_f32_e32 v1, v1, v2
	v_add_f32_e32 v0, v0, v1
	v_mul_f32_e32 v1, v17, v17
	v_mul_f32_e32 v2, v19, v19
	v_fmac_f32_e32 v1, v16, v16
	v_fmac_f32_e32 v2, v18, v18
	v_add_f32_e32 v1, v1, v2
	v_add_f32_e32 v0, v0, v1
	v_mul_f32_e32 v1, v13, v13
	v_mul_f32_e32 v2, v15, v15
	v_fmac_f32_e32 v1, v12, v12
	v_fmac_f32_e32 v2, v14, v14
	v_add_f32_e32 v1, v1, v2
	v_add_f32_e32 v0, v0, v1
	v_mov_b32_e32 v1, v0
	s_nop 1
	v_permlane16_swap_b32_e32 v0, v1
	v_add_f32_e32 v2, v0, v1
	v_mov_b32_e32 v178, v2
	s_nop 1
	v_permlane32_swap_b32_e32 v2, v178
	s_and_saveexec_b64 s[4:5], s[38:39]
	s_cbranch_execz .LBB0_57
	v_add_f32_e32 v0, v2, v178
	ds_write_b32 v172, v0 offset:512
.LBB0_57:
	s_or_b64 exec, exec, s[4:5]
	v_mul_f32_e32 v0, v41, v41
	v_mul_f32_e32 v1, v43, v43
	v_fmac_f32_e32 v0, v40, v40
	v_fmac_f32_e32 v1, v42, v42
	v_add_f32_e32 v0, v0, v1
	v_mul_f32_e32 v1, v37, v37
	v_mul_f32_e32 v2, v39, v39
	v_fmac_f32_e32 v1, v36, v36
	v_fmac_f32_e32 v2, v38, v38
	v_add_f32_e32 v1, v1, v2
	v_add_f32_e32 v0, v0, v1
	v_mul_f32_e32 v1, v9, v9
	v_mul_f32_e32 v2, v11, v11
	v_fmac_f32_e32 v1, v8, v8
	v_fmac_f32_e32 v2, v10, v10
	v_add_f32_e32 v1, v1, v2
	v_add_f32_e32 v0, v0, v1
	v_mul_f32_e32 v1, v5, v5
	v_mul_f32_e32 v2, v7, v7
	v_fmac_f32_e32 v1, v4, v4
	v_fmac_f32_e32 v2, v6, v6
	v_add_f32_e32 v1, v1, v2
	v_add_f32_e32 v0, v0, v1
	v_mov_b32_e32 v1, v0
	s_nop 1
	v_permlane16_swap_b32_e32 v0, v1
	v_add_f32_e32 v2, v0, v1
	v_mov_b32_e32 v178, v2
	s_nop 1
	v_permlane32_swap_b32_e32 v2, v178
	s_and_saveexec_b64 s[4:5], s[38:39]
	s_cbranch_execz .LBB0_59
	v_add_f32_e32 v0, v2, v178
	ds_write_b32 v172, v0 offset:768

.LBB0_116:
	s_add_i32 s4, s9, 5
	s_mul_hi_i32 s5, s4, 0x6000
	s_mulk_i32 s4, 0x6000
	s_add_u32 s4, s83, s4
	s_addc_u32 s5, s84, s5
	s_add_u32 s8, s4, 0x1000
	s_addc_u32 s9, s5, 0
	v_lshl_add_u64 v[68:69], s[62:63], 0, v[148:149]
	v_lshl_add_u64 v[70:71], s[8:9], 0, v[148:149]
	v_lshl_add_u64 v[116:117], s[4:5], 0, v[148:149]
	global_load_dwordx4 v[108:111], v[70:71], off
	global_load_dwordx4 v[76:79], v[116:117], off
	global_load_dwordx4 v[100:103], v[68:69], off
	global_load_dwordx4 v[88:91], v[68:69], off offset:64
	v_lshl_add_u64 v[70:71], v[150:151], 2, s[8:9]
	v_lshl_add_u64 v[96:97], v[152:153], 2, s[8:9]
	global_load_dwordx4 v[80:83], v[116:117], off offset:64
	global_load_dwordx4 v[72:75], v[116:117], off offset:512
	global_load_dwordx4 v[92:95], v[68:69], off offset:512
	global_load_dwordx4 v[84:87], v[68:69], off offset:576
	v_lshl_add_u64 v[68:69], v[154:155], 2, s[8:9]
	global_load_dwordx4 v[104:107], v[96:97], off
	s_nop 0
	global_load_dwordx4 v[96:99], v[68:69], off
	global_load_dwordx4 v[112:115], v[70:71], off
	s_nop 0
	global_load_dwordx4 v[68:71], v[116:117], off offset:576
	v_mul_f32_e32 v0, v61, v61
	v_mul_f32_e32 v1, v63, v63
	v_fmac_f32_e32 v0, v60, v60
	v_fmac_f32_e32 v1, v62, v62
	v_add_f32_e32 v0, v0, v1
	v_mul_f32_e32 v1, v65, v65
	v_mul_f32_e32 v2, v67, v67
	v_fmac_f32_e32 v1, v64, v64
	v_fmac_f32_e32 v2, v66, v66
	v_add_f32_e32 v1, v1, v2
	v_add_f32_e32 v0, v0, v1
	v_mul_f32_e32 v1, v33, v33
	v_mul_f32_e32 v2, v35, v35
	v_fmac_f32_e32 v1, v32, v32
	v_fmac_f32_e32 v2, v34, v34
	v_add_f32_e32 v1, v1, v2
	v_add_f32_e32 v0, v1, v0
	v_mul_f32_e32 v1, v29, v29
	v_mul_f32_e32 v2, v31, v31
	v_fmac_f32_e32 v1, v28, v28
	v_fmac_f32_e32 v2, v30, v30
	v_add_f32_e32 v1, v1, v2
	v_add_f32_e32 v0, v1, v0
	v_mov_b32_e32 v1, v0
	s_nop 1
	v_permlane16_swap_b32_e32 v0, v1
	v_add_f32_e32 v2, v0, v1
	v_mov_b32_e32 v116, v2
	s_nop 1
	v_permlane32_swap_b32_e32 v2, v116
	s_and_saveexec_b64 s[4:5], s[38:39]
	s_cbranch_execz .LBB0_118
	v_add_f32_e32 v0, v2, v116
	ds_write_b32 v172, v0
.LBB0_118:
	s_or_b64 exec, exec, s[4:5]
	v_mul_f32_e32 v0, v57, v57
	v_mul_f32_e32 v1, v59, v59
	v_fmac_f32_e32 v0, v56, v56
	v_fmac_f32_e32 v1, v58, v58
	v_add_f32_e32 v0, v0, v1
	v_mul_f32_e32 v1, v53, v53
	v_mul_f32_e32 v2, v55, v55
	v_fmac_f32_e32 v1, v52, v52
	v_fmac_f32_e32 v2, v54, v54
	v_add_f32_e32 v1, v1, v2
	v_add_f32_e32 v0, v0, v1
	v_mul_f32_e32 v1, v25, v25
	v_mul_f32_e32 v2, v27, v27
	v_fmac_f32_e32 v1, v24, v24
	v_fmac_f32_e32 v2, v26, v26
	v_add_f32_e32 v1, v1, v2
	v_add_f32_e32 v0, v1, v0
	v_mul_f32_e32 v1, v21, v21
	v_mul_f32_e32 v2, v23, v23
	v_fmac_f32_e32 v1, v20, v20
	v_fmac_f32_e32 v2, v22, v22
	v_add_f32_e32 v1, v1, v2
	v_add_f32_e32 v0, v1, v0
	v_mov_b32_e32 v1, v0
	s_nop 1
	v_permlane16_swap_b32_e32 v0, v1
	v_add_f32_e32 v2, v0, v1
	v_mov_b32_e32 v116, v2
	s_nop 1
	v_permlane32_swap_b32_e32 v2, v116
	s_and_saveexec_b64 s[4:5], s[38:39]
	s_cbranch_execz .LBB0_120
	v_add_f32_e32 v0, v2, v116
	ds_write_b32 v172, v0 offset:256
.LBB0_120:
	s_or_b64 exec, exec, s[4:5]
	v_mul_f32_e32 v0, v49, v49
	v_mul_f32_e32 v1, v51, v51
	v_fmac_f32_e32 v0, v48, v48
	v_fmac_f32_e32 v1, v50, v50
	v_add_f32_e32 v0, v0, v1
	v_mul_f32_e32 v1, v45, v45
	v_mul_f32_e32 v2, v47, v47
	v_fmac_f32_e32 v1, v44, v44
	v_fmac_f32_e32 v2, v46, v46
	v_add_f32_e32 v1, v1, v2
	v_add_f32_e32 v0, v0, v1
	v_mul_f32_e32 v1, v17, v17
	v_mul_f32_e32 v2, v19, v19
	v_fmac_f32_e32 v1, v16, v16
	v_fmac_f32_e32 v2, v18, v18
	v_add_f32_e32 v1, v1, v2
	v_add_f32_e32 v0, v1, v0
	v_mul_f32_e32 v1, v13, v13
	v_mul_f32_e32 v2, v15, v15
	v_fmac_f32_e32 v1, v12, v12
	v_fmac_f32_e32 v2, v14, v14
	v_add_f32_e32 v1, v1, v2
	v_add_f32_e32 v0, v1, v0
	v_mov_b32_e32 v1, v0
	s_nop 1
	v_permlane16_swap_b32_e32 v0, v1
	v_add_f32_e32 v2, v0, v1
	v_mov_b32_e32 v116, v2
	s_nop 1
	v_permlane32_swap_b32_e32 v2, v116
	s_and_saveexec_b64 s[4:5], s[38:39]
	s_cbranch_execz .LBB0_122
	v_add_f32_e32 v0, v2, v116
	ds_write_b32 v172, v0 offset:512
.LBB0_122:
	s_or_b64 exec, exec, s[4:5]
	v_mul_f32_e32 v0, v41, v41
	v_mul_f32_e32 v1, v43, v43
	v_fmac_f32_e32 v0, v40, v40
	v_fmac_f32_e32 v1, v42, v42
	v_add_f32_e32 v0, v0, v1
	v_mul_f32_e32 v1, v37, v37
	v_mul_f32_e32 v2, v39, v39
	v_fmac_f32_e32 v1, v36, v36
	v_fmac_f32_e32 v2, v38, v38
	v_add_f32_e32 v1, v1, v2
	v_add_f32_e32 v0, v0, v1
	v_mul_f32_e32 v1, v9, v9
	v_mul_f32_e32 v2, v11, v11
	v_fmac_f32_e32 v1, v8, v8
	v_fmac_f32_e32 v2, v10, v10
	v_add_f32_e32 v1, v1, v2
	v_add_f32_e32 v0, v1, v0
	v_mul_f32_e32 v1, v5, v5
	v_mul_f32_e32 v2, v7, v7
	v_fmac_f32_e32 v1, v4, v4
	v_fmac_f32_e32 v2, v6, v6
	v_add_f32_e32 v1, v1, v2
	v_add_f32_e32 v0, v1, v0
	v_mov_b32_e32 v1, v0
	s_nop 1
	v_permlane16_swap_b32_e32 v0, v1
	v_add_f32_e32 v2, v0, v1
	v_mov_b32_e32 v116, v2
	s_nop 1
	v_permlane32_swap_b32_e32 v2, v116
	s_and_saveexec_b64 s[4:5], s[38:39]
	s_cbranch_execz .LBB0_124
	v_add_f32_e32 v0, v2, v116
	ds_write_b32 v172, v0 offset:768

.LBB0_435:
	s_add_i32 s4, s74, 0xfffff000
	s_ashr_i32 s4, s4, 10
	s_add_i32 s4, s4, 1
	s_cmp_gt_i32 s8, 31
	v_readlane_b32 s2, v254, 57
	s_cselect_b32 s4, s4, 0
	s_mul_i32 s5, s2, 5
	s_add_i32 s4, s4, s5
	s_mul_hi_i32 s5, s4, 0x6000
	s_mulk_i32 s4, 0x6000
	s_add_u32 s9, s87, s4
	s_addc_u32 s20, s88, s5
	s_add_u32 s4, s9, 0x2000
	v_or_b32_e32 v182, 16, v188
	v_or_b32_e32 v186, 0x80, v188
	v_or_b32_e32 v184, 0x90, v188
	s_addc_u32 s5, s20, 0
	v_lshlrev_b64 v[180:181], 2, v[188:189]
	v_ashrrev_i32_e32 v183, 31, v182
	v_ashrrev_i32_e32 v187, 31, v186
	v_ashrrev_i32_e32 v185, 31, v184
	v_lshl_add_u64 v[132:133], s[6:7], 0, v[180:181]
	v_lshl_add_u64 v[134:135], s[4:5], 0, v[180:181]
	v_lshl_add_u64 v[136:137], v[182:183], 2, s[4:5]
	v_lshl_add_u64 v[140:141], v[186:187], 2, s[4:5]
	v_lshl_add_u64 v[142:143], v[184:185], 2, s[4:5]
	global_load_dwordx4 v[148:151], v[132:133], off
	global_load_dwordx4 v[152:155], v[132:133], off offset:64
	global_load_dwordx4 v[160:163], v[134:135], off
	global_load_dwordx4 v[156:159], v[136:137], off
	s_nop 0
	global_load_dwordx4 v[136:139], v[132:133], off offset:512
	s_nop 0
	global_load_dwordx4 v[132:135], v[132:133], off offset:576
	s_nop 0
	global_load_dwordx4 v[144:147], v[140:141], off
	s_nop 0
	global_load_dwordx4 v[140:143], v[142:143], off
	v_mul_f32_e32 v0, v65, v65
	v_mul_f32_e32 v1, v67, v67
	v_fmac_f32_e32 v0, v64, v64
	v_fmac_f32_e32 v1, v66, v66
	v_add_f32_e32 v0, v0, v1
	v_mul_f32_e32 v1, v61, v61
	v_mul_f32_e32 v2, v63, v63
	v_fmac_f32_e32 v1, v60, v60
	v_fmac_f32_e32 v2, v62, v62
	v_add_f32_e32 v1, v1, v2
	v_add_f32_e32 v0, v0, v1
	v_mul_f32_e32 v1, v33, v33
	v_mul_f32_e32 v2, v35, v35
	v_fmac_f32_e32 v1, v32, v32
	v_fmac_f32_e32 v2, v34, v34
	v_add_f32_e32 v1, v1, v2
	v_add_f32_e32 v0, v0, v1
	v_mul_f32_e32 v1, v29, v29
	v_mul_f32_e32 v2, v31, v31
	v_fmac_f32_e32 v1, v28, v28
	v_fmac_f32_e32 v2, v30, v30
	v_add_f32_e32 v1, v1, v2
	v_add_f32_e32 v0, v0, v1
	v_mov_b32_e32 v1, v0
	s_nop 1
	v_permlane16_swap_b32_e32 v0, v1
	v_add_f32_e32 v2, v0, v1
	v_mov_b32_e32 v232, v2
	s_nop 1
	v_permlane32_swap_b32_e32 v2, v232
	s_and_saveexec_b64 s[4:5], s[38:39]
	s_cbranch_execz .LBB0_437
	v_add_f32_e32 v0, v2, v232
	ds_write_b32 v226, v0
.LBB0_437:
	s_or_b64 exec, exec, s[4:5]
	v_mul_f32_e32 v0, v57, v57
	v_mul_f32_e32 v1, v59, v59
	v_fmac_f32_e32 v0, v56, v56
	v_fmac_f32_e32 v1, v58, v58
	v_add_f32_e32 v0, v0, v1
	v_mul_f32_e32 v1, v53, v53
	v_mul_f32_e32 v2, v55, v55
	v_fmac_f32_e32 v1, v52, v52
	v_fmac_f32_e32 v2, v54, v54
	v_add_f32_e32 v1, v1, v2
	v_add_f32_e32 v0, v0, v1
	v_mul_f32_e32 v1, v25, v25
	v_mul_f32_e32 v2, v27, v27
	v_fmac_f32_e32 v1, v24, v24
	v_fmac_f32_e32 v2, v26, v26
	v_add_f32_e32 v1, v1, v2
	v_add_f32_e32 v0, v0, v1
	v_mul_f32_e32 v1, v21, v21
	v_mul_f32_e32 v2, v23, v23
	v_fmac_f32_e32 v1, v20, v20
	v_fmac_f32_e32 v2, v22, v22
	v_add_f32_e32 v1, v1, v2
	v_add_f32_e32 v0, v0, v1
	v_mov_b32_e32 v1, v0
	s_nop 1
	v_permlane16_swap_b32_e32 v0, v1
	v_add_f32_e32 v2, v0, v1
	v_mov_b32_e32 v232, v2
	s_nop 1
	v_permlane32_swap_b32_e32 v2, v232
	s_and_saveexec_b64 s[4:5], s[38:39]
	s_cbranch_execz .LBB0_439
	v_add_f32_e32 v0, v2, v232
	ds_write_b32 v226, v0 offset:256
.LBB0_439:
	s_or_b64 exec, exec, s[4:5]
	v_mul_f32_e32 v0, v49, v49
	v_mul_f32_e32 v1, v51, v51
	v_fmac_f32_e32 v0, v48, v48
	v_fmac_f32_e32 v1, v50, v50
	v_add_f32_e32 v0, v0, v1
	v_mul_f32_e32 v1, v45, v45
	v_mul_f32_e32 v2, v47, v47
	v_fmac_f32_e32 v1, v44, v44
	v_fmac_f32_e32 v2, v46, v46
	v_add_f32_e32 v1, v1, v2
	v_add_f32_e32 v0, v0, v1
	v_mul_f32_e32 v1, v17, v17
	v_mul_f32_e32 v2, v19, v19
	v_fmac_f32_e32 v1, v16, v16
	v_fmac_f32_e32 v2, v18, v18
	v_add_f32_e32 v1, v1, v2
	v_add_f32_e32 v0, v0, v1
	v_mul_f32_e32 v1, v13, v13
	v_mul_f32_e32 v2, v15, v15
	v_fmac_f32_e32 v1, v12, v12
	v_fmac_f32_e32 v2, v14, v14
	v_add_f32_e32 v1, v1, v2
	v_add_f32_e32 v0, v0, v1
	v_mov_b32_e32 v1, v0
	s_nop 1
	v_permlane16_swap_b32_e32 v0, v1
	v_add_f32_e32 v2, v0, v1
	v_mov_b32_e32 v232, v2
	s_nop 1
	v_permlane32_swap_b32_e32 v2, v232
	s_and_saveexec_b64 s[4:5], s[38:39]
	s_cbranch_execz .LBB0_441
	v_add_f32_e32 v0, v2, v232
	ds_write_b32 v226, v0 offset:512
.LBB0_441:
	s_or_b64 exec, exec, s[4:5]
	v_mul_f32_e32 v0, v41, v41
	v_mul_f32_e32 v1, v43, v43
	v_fmac_f32_e32 v0, v40, v40
	v_fmac_f32_e32 v1, v42, v42
	v_add_f32_e32 v0, v0, v1
	v_mul_f32_e32 v1, v37, v37
	v_mul_f32_e32 v2, v39, v39
	v_fmac_f32_e32 v1, v36, v36
	v_fmac_f32_e32 v2, v38, v38
	v_add_f32_e32 v1, v1, v2
	v_add_f32_e32 v0, v0, v1
	v_mul_f32_e32 v1, v9, v9
	v_mul_f32_e32 v2, v11, v11
	v_fmac_f32_e32 v1, v8, v8
	v_fmac_f32_e32 v2, v10, v10
	v_add_f32_e32 v1, v1, v2
	v_add_f32_e32 v0, v0, v1
	v_mul_f32_e32 v1, v5, v5
	v_mul_f32_e32 v2, v7, v7
	v_fmac_f32_e32 v1, v4, v4
	v_fmac_f32_e32 v2, v6, v6
	v_add_f32_e32 v1, v1, v2
	v_add_f32_e32 v0, v0, v1
	v_mov_b32_e32 v1, v0
	s_nop 1
	v_permlane16_swap_b32_e32 v0, v1
	v_add_f32_e32 v2, v0, v1
	v_mov_b32_e32 v232, v2
	s_nop 1
	v_permlane32_swap_b32_e32 v2, v232
	s_and_saveexec_b64 s[4:5], s[38:39]
	s_cbranch_execz .LBB0_443
	v_add_f32_e32 v0, v2, v232
	ds_write_b32 v226, v0 offset:768

.LBB0_497:
	s_add_u32 s4, s9, 0x3000
	s_addc_u32 s5, s20, 0
	s_add_u32 s8, s9, 0x4000
	s_addc_u32 s9, s20, 0
	v_lshl_add_u64 v[68:69], s[8:9], 0, v[180:181]
	v_lshl_add_u64 v[72:73], s[66:67], 0, v[180:181]
	v_lshl_add_u64 v[70:71], s[4:5], 0, v[180:181]
	global_load_dwordx4 v[108:111], v[68:69], off
	global_load_dwordx4 v[76:79], v[70:71], off
	global_load_dwordx4 v[96:99], v[72:73], off
	global_load_dwordx4 v[88:91], v[72:73], off offset:64
	v_lshlrev_b64 v[68:69], 2, v[182:183]
	v_lshl_add_u64 v[70:71], s[8:9], 0, v[68:69]
	v_lshl_add_u64 v[68:69], s[4:5], 0, v[68:69]
	global_load_dwordx4 v[112:115], v[70:71], off
	global_load_dwordx4 v[80:83], v[68:69], off
	v_lshlrev_b64 v[68:69], 2, v[186:187]
	v_lshl_add_u64 v[70:71], s[8:9], 0, v[68:69]
	v_lshl_add_u64 v[68:69], s[4:5], 0, v[68:69]
	global_load_dwordx4 v[100:103], v[70:71], off
	s_nop 0
	global_load_dwordx4 v[68:71], v[68:69], off
	s_nop 0
	global_load_dwordx4 v[92:95], v[72:73], off offset:512
	global_load_dwordx4 v[84:87], v[72:73], off offset:576
	v_lshlrev_b64 v[72:73], 2, v[184:185]
	v_lshl_add_u64 v[74:75], s[8:9], 0, v[72:73]
	v_lshl_add_u64 v[72:73], s[4:5], 0, v[72:73]
	global_load_dwordx4 v[104:107], v[74:75], off
	s_nop 0
	global_load_dwordx4 v[72:75], v[72:73], off
	v_mul_f32_e32 v0, v65, v65
	v_mul_f32_e32 v1, v67, v67
	v_fmac_f32_e32 v0, v64, v64
	v_fmac_f32_e32 v1, v66, v66
	v_add_f32_e32 v0, v0, v1
	v_mul_f32_e32 v1, v61, v61
	v_mul_f32_e32 v2, v63, v63
	v_fmac_f32_e32 v1, v60, v60
	v_fmac_f32_e32 v2, v62, v62
	v_add_f32_e32 v1, v1, v2
	v_add_f32_e32 v0, v0, v1
	v_mul_f32_e32 v1, v33, v33
	v_mul_f32_e32 v2, v35, v35
	v_fmac_f32_e32 v1, v32, v32
	v_fmac_f32_e32 v2, v34, v34
	v_add_f32_e32 v1, v1, v2
	v_add_f32_e32 v0, v1, v0
	v_mul_f32_e32 v1, v29, v29
	v_mul_f32_e32 v2, v31, v31
	v_fmac_f32_e32 v1, v28, v28
	v_fmac_f32_e32 v2, v30, v30
	v_add_f32_e32 v1, v1, v2
	v_add_f32_e32 v0, v1, v0
	v_mov_b32_e32 v1, v0
	s_nop 1
	v_permlane16_swap_b32_e32 v0, v1
	v_add_f32_e32 v2, v0, v1
	v_mov_b32_e32 v120, v2
	s_nop 1
	v_permlane32_swap_b32_e32 v2, v120
	s_and_saveexec_b64 s[4:5], s[38:39]
	s_cbranch_execz .LBB0_499
	v_add_f32_e32 v0, v2, v120
	ds_write_b32 v226, v0
.LBB0_499:
	s_or_b64 exec, exec, s[4:5]
	v_mul_f32_e32 v0, v57, v57
	v_mul_f32_e32 v1, v59, v59
	v_fmac_f32_e32 v0, v56, v56
	v_fmac_f32_e32 v1, v58, v58
	v_add_f32_e32 v0, v0, v1
	v_mul_f32_e32 v1, v53, v53
	v_mul_f32_e32 v2, v55, v55
	v_fmac_f32_e32 v1, v52, v52
	v_fmac_f32_e32 v2, v54, v54
	v_add_f32_e32 v1, v1, v2
	v_add_f32_e32 v0, v0, v1
	v_mul_f32_e32 v1, v25, v25
	v_mul_f32_e32 v2, v27, v27
	v_fmac_f32_e32 v1, v24, v24
	v_fmac_f32_e32 v2, v26, v26
	v_add_f32_e32 v1, v1, v2
	v_add_f32_e32 v0, v1, v0
	v_mul_f32_e32 v1, v21, v21
	v_mul_f32_e32 v2, v23, v23
	v_fmac_f32_e32 v1, v20, v20
	v_fmac_f32_e32 v2, v22, v22
	v_add_f32_e32 v1, v1, v2
	v_add_f32_e32 v0, v1, v0
	v_mov_b32_e32 v1, v0
	s_nop 1
	v_permlane16_swap_b32_e32 v0, v1
	v_add_f32_e32 v2, v0, v1
	v_mov_b32_e32 v120, v2
	s_nop 1
	v_permlane32_swap_b32_e32 v2, v120
	s_and_saveexec_b64 s[4:5], s[38:39]
	s_cbranch_execz .LBB0_501
	v_add_f32_e32 v0, v2, v120
	ds_write_b32 v226, v0 offset:256
.LBB0_501:
	s_or_b64 exec, exec, s[4:5]
	v_mul_f32_e32 v0, v49, v49
	v_mul_f32_e32 v1, v51, v51
	v_fmac_f32_e32 v0, v48, v48
	v_fmac_f32_e32 v1, v50, v50
	v_add_f32_e32 v0, v0, v1
	v_mul_f32_e32 v1, v45, v45
	v_mul_f32_e32 v2, v47, v47
	v_fmac_f32_e32 v1, v44, v44
	v_fmac_f32_e32 v2, v46, v46
	v_add_f32_e32 v1, v1, v2
	v_add_f32_e32 v0, v0, v1
	v_mul_f32_e32 v1, v17, v17
	v_mul_f32_e32 v2, v19, v19
	v_fmac_f32_e32 v1, v16, v16
	v_fmac_f32_e32 v2, v18, v18
	v_add_f32_e32 v1, v1, v2
	v_add_f32_e32 v0, v1, v0
	v_mul_f32_e32 v1, v13, v13
	v_mul_f32_e32 v2, v15, v15
	v_fmac_f32_e32 v1, v12, v12
	v_fmac_f32_e32 v2, v14, v14
	v_add_f32_e32 v1, v1, v2
	v_add_f32_e32 v0, v1, v0
	v_mov_b32_e32 v1, v0
	s_nop 1
	v_permlane16_swap_b32_e32 v0, v1
	v_add_f32_e32 v2, v0, v1
	v_mov_b32_e32 v120, v2
	s_nop 1
	v_permlane32_swap_b32_e32 v2, v120
	s_and_saveexec_b64 s[4:5], s[38:39]
	s_cbranch_execz .LBB0_503
	v_add_f32_e32 v0, v2, v120
	ds_write_b32 v226, v0 offset:512
.LBB0_503:
	s_or_b64 exec, exec, s[4:5]
	v_mul_f32_e32 v0, v41, v41
	v_mul_f32_e32 v1, v43, v43
	v_fmac_f32_e32 v0, v40, v40
	v_fmac_f32_e32 v1, v42, v42
	v_add_f32_e32 v0, v0, v1
	v_mul_f32_e32 v1, v37, v37
	v_mul_f32_e32 v2, v39, v39
	v_fmac_f32_e32 v1, v36, v36
	v_fmac_f32_e32 v2, v38, v38
	v_add_f32_e32 v1, v1, v2
	v_add_f32_e32 v0, v0, v1
	v_mul_f32_e32 v1, v9, v9
	v_mul_f32_e32 v2, v11, v11
	v_fmac_f32_e32 v1, v8, v8
	v_fmac_f32_e32 v2, v10, v10
	v_add_f32_e32 v1, v1, v2
	v_add_f32_e32 v0, v1, v0
	v_mul_f32_e32 v1, v5, v5
	v_mul_f32_e32 v2, v7, v7
	v_fmac_f32_e32 v1, v4, v4
	v_fmac_f32_e32 v2, v6, v6
	v_add_f32_e32 v1, v1, v2
	v_add_f32_e32 v0, v1, v0
	v_mov_b32_e32 v1, v0
	s_nop 1
	v_permlane16_swap_b32_e32 v0, v1
	v_add_f32_e32 v2, v0, v1
	v_mov_b32_e32 v120, v2
	s_nop 1
	v_permlane32_swap_b32_e32 v2, v120
	s_and_saveexec_b64 s[4:5], s[38:39]
	s_cbranch_execz .LBB0_505
	v_add_f32_e32 v0, v2, v120
	ds_write_b32 v226, v0 offset:768
